# phase 1 writes each workgroup's own row panel so the ph1 to FFN-in seam is a 4-CU panel barrier instead of a global one
# speedup vs baseline: 1.0214x; 1.0124x over previous
; __device__ __forceinline__ int otid() { int t = (int)threadIdx.x; asm volatile("" : "+v"(t)); return t; }
; __device__ __forceinline__ void p1_phase(CA& A) {
;     const int tid = otid(), lane = tid & 63, wave = __builtin_amdgcn_readfirstlane(tid >> 6);
;     const int gw = blockIdx.x * 8 + wave, NGW = gridDim.x * 8;
;     const float* MOD = (const float*)(A.ws + WS_MOD);
;     bf16_t* XN = (bf16_t*)(A.ws + WS_XN);
;     for (int grp = gw; grp < M / 8; grp += NGW) {
;         const int row0 = grp * 8, b = row0 >> 12;
;         f32x4 ca[4], cb[4];
; #pragma unroll
;         for (int j = 0; j < 4; ++j) { const int col = 4 * lane + 256 * j;
;             ca[j] = *(const f32x4*)(A.norm_g + col) * (1.0f + *(const f32x4*)(MOD + (size_t)b * NMODC + DM + col)); cb[j] = *(const f32x4*)(MOD + (size_t)b * NMODC + col); }
; __global__ void __launch_bounds__(512, 2) fwd_kernel(Args A_unused) {
;     ...
;     for (int ph = ph_lo; ph < ph_hi; ++ph) {
;         CA* P = P0; asm volatile("" : "+s"(P)); CA& A = *P;
;         bf16_t* XN = (bf16_t*)(A.ws + WS_XN); bf16_t* ACT = (bf16_t*)(A.ws + WS_ACT); bf16_t* Zp = (bf16_t*)(A.ws + WS_Z); bf16_t* MIXp = (bf16_t*)(A.ws + WS_MIX);
;         const float* MOD = (const float*)(A.ws + WS_MOD);
;         if (ph == 0) { p0_prologue(A, lds); }
;         else if (ph == 1) { p1_phase(A); }
.LBB0_10:
	v_readlane_b32 s4, v238, 2
	v_readlane_b32 s5, v238, 3
	v_readlane_b32 s6, v238, 0
	v_writelane_b32 v237, s4, 63
	v_readlane_b32 s7, v238, 1
	s_waitcnt lgkmcnt(0)
	s_mov_b64 s[8:9], -1
	v_writelane_b32 v236, s5, 0
	s_load_dwordx2 s[4:5], s[4:5], 0xc8
	s_cmp_lt_i32 s6, 1
	s_mov_b64 s[6:7], 0
	s_waitcnt lgkmcnt(0)
	v_writelane_b32 v236, s4, 1
	s_nop 1
	v_writelane_b32 v236, s5, 2
	s_mov_b64 s[4:5], 0
	s_cbranch_scc1 .LBB0_24
	v_readlane_b32 s6, v238, 0
	v_readlane_b32 s7, v238, 1
	s_cmp_eq_u32 s6, 1
	s_mov_b64 s[6:7], -1
	s_cbranch_scc0 .LBB0_18
	v_mov_b32_e32 v1, v179
	v_readlane_b32 s7, v237, 62
	s_nop 1
	s_and_b32 s18, s7, 7
	s_lshl_b32 s18, s18, 5
	s_bfe_u32 s19, s7, 0x30003
	s_lshl_b32 s19, s19, 2
	s_add_i32 s18, s18, s19
	s_lshr_b32 s7, s7, 6
	s_add_i32 s7, s18, s7
	s_lshl_b32 s7, s7, 3
	v_readfirstlane_b32 s6, v1
	s_ashr_i32 s6, s6, 6
	s_add_i32 s10, s6, s7
	s_cmpk_gt_i32 s10, 0x7ff
	s_cbranch_scc1 .LBB0_17
	v_readlane_b32 s14, v237, 63
	v_readlane_b32 s15, v236, 0
	s_load_dwordx2 s[8:9], s[14:15], 0x0
	s_nop 0
	s_load_dwordx2 s[14:15], s[14:15], 0x20
	v_readlane_b32 s16, v236, 1
	v_lshlrev_b32_e32 v2, 2, v1
	v_and_b32_e32 v1, 63, v1
	v_readlane_b32 s17, v236, 2
	v_and_b32_e32 v2, 0xfc, v2
	v_lshlrev_b32_e32 v10, 3, v1
	v_mov_b32_e32 v11, v0
	s_add_u32 s11, s16, 0x10000
	v_lshlrev_b32_e32 v4, 2, v2
	v_mov_b32_e32 v5, v0
	v_lshl_add_u64 v[20:21], s[16:17], 0, v[10:11]
	v_lshlrev_b32_e32 v10, 4, v1
	s_addc_u32 s12, s17, 0
	s_waitcnt lgkmcnt(0)
	v_lshl_add_u64 v[18:19], s[14:15], 0, v[4:5]
	v_or_b32_e32 v4, 0x100, v2
	v_or_b32_e32 v6, 0x200, v2
	v_or_b32_e32 v8, 0x300, v2
	s_lshl_b32 s6, s6, 3
	s_lshl_b32 s7, s10, 3
	s_sub_i32 s7, s7, s6
	v_lshl_add_u64 v[10:11], s[8:9], 0, v[10:11]
	s_mov_b64 s[8:9], 0x800
	s_add_i32 s6, s7, s6
	v_lshl_add_u64 v[22:23], v[10:11], 0, s[8:9]
	v_lshlrev_b32_e32 v1, 2, v2
	v_lshlrev_b32_e32 v44, 2, v4
	v_lshlrev_b32_e32 v45, 2, v6
	v_lshlrev_b32_e32 v46, 2, v8

; __device__ __forceinline__ void xcd_barrier(const XcdBarrier& b) {
;     asm volatile("s_waitcnt vmcnt(0)" ::: "memory");
;     __syncthreads();
;     if (threadIdx.x == 0) {
; __global__ void __launch_bounds__(512, 2) fwd_kernel(Args A_unused) {
;     ...
;         if (ph + 1 < ph_hi) {
;             if (ph_lo < 0) grid.sync();
;             xcd_barrier(xbar);
;         }
.LBB0_893:
	v_mov_b32_e32 v1, 0x20018
	ds_read_b32 v1, v1
	v_readlane_b32 s10, v238, 0
	v_readlane_b32 s13, v237, 62
	s_waitcnt vmcnt(0) lgkmcnt(0)
	s_nop 0
	v_readfirstlane_b32 s11, v1
	s_nop 3
	s_mul_i32 s11, s11, 0xcd9c
	s_bitcmp1_b32 s11, s10
	s_cbranch_scc0 .Lmy_global_bar
	s_lshl_b32 s12, 2, s10
	s_add_i32 s12, s12, -1
	s_and_b32 s12, s12, 0xcd9c
	s_bcnt1_i32_b32 s12, s12
	s_lshl_b32 s12, s12, 2
	s_and_b32 s6, s13, 7
	s_lshl_b32 s6, s6, 3
	s_bfe_u32 s7, s13, 0x30003
	s_add_i32 s13, s6, s7
	s_mul_i32 s6, s13, 10
	s_mul_i32 s6, s6, 0x1746
	s_lshr_b32 s6, s6, 16
	s_add_i32 s7, s6, 1
	s_min_u32 s7, s7, s13
	s_cmp_eq_u32 s10, 4
	s_cselect_b32 s11, 1, 0
	s_cmp_eq_u32 s10, 11
	s_cselect_b32 s11, 1, s11
	s_cmp_eq_u32 s11, 1
	s_cselect_b32 s6, s6, s13
	s_cselect_b32 s7, s7, s13
	s_lshl_b32 s13, s13, 6
	s_lshl_b32 s6, s6, 6
	s_lshl_b32 s7, s7, 6
	s_addk_i32 s13, 0x1000
	s_addk_i32 s6, 0x1000
	s_addk_i32 s7, 0x1000
	v_mov_b32_e32 v1, s13
	v_mov_b32_e32 v2, s6
	v_mov_b32_e32 v3, s7
	v_readlane_b32 s6, v238, 30
	v_readlane_b32 s7, v238, 31
	v_mov_b32_e32 v8, 1
	s_mov_b32 s13, 0
	s_sub_u32 s6, s6, 0x4200
	s_subb_u32 s7, s7, 0
	s_nop 4
	global_atomic_add v1, v8, s[6:7]
